# v22 + nt hint on the final norm's f32 output stores (write-once, end of kernel)
# baseline (speedup 1.0000x reference)
; __device__ __forceinline__ f32x4 unpack4(unsigned long long w) { const unsigned lo = (unsigned)w, hi = (unsigned)(w >> 32); return (f32x4){__uint_as_float(lo << 16), __uint_as_float(lo & 0xffff0000u), __uint_as_float(hi << 16), __uint_as_float(hi & 0xffff0000u)}; }
; template <int MODE, int NR>
; __device__ __forceinline__ void norm_rows(const float* X32, bf16* X, bf16* H, float* out32, const f32x4 (&mul)[4], const f32x4 (&sh)[4], int lane) {
;     ...
;         unsigned long long raw[NR][4];
; #pragma unroll
;         for (int r = 0; r < NR; ++r) { const unsigned long long* xr = (const unsigned long long*)(X + (size_t)r * D) + lane;
; #pragma unroll
;             for (int j = 0; j < 4; ++j) raw[r][j] = xr[64 * j]; }
; #pragma unroll
;         for (int r = 0; r < NR; ++r) { f32x4 v[4]; float s = 0.f;
; #pragma unroll
;             for (int j = 0; j < 4; ++j) { v[j] = unpack4(raw[r][j]); s += (v[j].x * v[j].x + v[j].y * v[j].y) + (v[j].z * v[j].z + v[j].w * v[j].w); }
.LBB0_1323:
	v_add_co_u32_e32 v34, vcc, 0xffffc200, v22
	v_add_co_u32_e64 v28, s[0:1], s5, v20
	s_nop 0
	v_addc_co_u32_e32 v35, vcc, -1, v23, vcc
	v_add_co_u32_e32 v42, vcc, 0xffffc400, v22
	v_addc_co_u32_e64 v29, s[0:1], 0, v21, s[0:1]
	s_nop 0
	v_addc_co_u32_e32 v43, vcc, -1, v23, vcc
	v_add_co_u32_e32 v44, vcc, 0xffffc600, v22
	global_load_dwordx2 v[46:47], v[34:35], off
	global_load_dwordx2 v[48:49], v[42:43], off
	v_addc_co_u32_e32 v45, vcc, -1, v23, vcc
	v_add_co_u32_e32 v34, vcc, 0xffffc800, v22
	v_add_co_u32_e64 v26, s[0:1], s6, v20
	s_nop 0
	v_addc_co_u32_e32 v35, vcc, -1, v23, vcc
	v_add_co_u32_e32 v42, vcc, 0xffffca00, v22
	global_load_dwordx2 v[50:51], v[44:45], off
	global_load_dwordx2 v[56:57], v[34:35], off
	v_addc_co_u32_e32 v43, vcc, -1, v23, vcc
	v_add_co_u32_e32 v34, vcc, 0xffffcc00, v22
	v_addc_co_u32_e64 v27, s[0:1], 0, v21, s[0:1]
	s_nop 0
	v_addc_co_u32_e32 v35, vcc, -1, v23, vcc
	v_add_co_u32_e32 v44, vcc, 0xffffce00, v22
	global_load_dwordx2 v[58:59], v[42:43], off
	global_load_dwordx2 v[64:65], v[34:35], off
	v_addc_co_u32_e32 v45, vcc, -1, v23, vcc
	v_add_co_u32_e32 v34, vcc, 0xffffd000, v22
	v_add_co_u32_e64 v32, s[0:1], s7, v20
	s_nop 0
	v_addc_co_u32_e32 v35, vcc, -1, v23, vcc
	v_add_co_u32_e32 v42, vcc, 0xffffd200, v22
	global_load_dwordx2 v[66:67], v[44:45], off
	global_load_dwordx2 v[72:73], v[34:35], off
	v_addc_co_u32_e32 v43, vcc, -1, v23, vcc
	v_add_co_u32_e32 v34, vcc, 0xffffd400, v22
	v_addc_co_u32_e64 v33, s[0:1], 0, v21, s[0:1]
	s_nop 0
	v_addc_co_u32_e32 v35, vcc, -1, v23, vcc
	v_add_co_u32_e32 v44, vcc, 0xffffd600, v22
	global_load_dwordx2 v[74:75], v[42:43], off
	global_load_dwordx2 v[76:77], v[34:35], off
	v_addc_co_u32_e32 v45, vcc, -1, v23, vcc
	v_add_co_u32_e32 v34, vcc, 0xffffd800, v22
	v_add_co_u32_e64 v30, s[0:1], s8, v20
	s_nop 0
	v_addc_co_u32_e32 v35, vcc, -1, v23, vcc
	v_add_co_u32_e32 v42, vcc, 0xffffda00, v22
	global_load_dwordx2 v[78:79], v[44:45], off
	global_load_dwordx2 v[84:85], v[34:35], off
	v_addc_co_u32_e32 v43, vcc, -1, v23, vcc
	v_add_co_u32_e32 v34, vcc, 0xffffdc00, v22
	v_addc_co_u32_e64 v31, s[0:1], 0, v21, s[0:1]
	s_nop 0
	v_addc_co_u32_e32 v35, vcc, -1, v23, vcc
	v_add_co_u32_e32 v44, vcc, 0xffffde00, v22
	global_load_dwordx2 v[88:89], v[42:43], off
	global_load_dwordx2 v[96:97], v[34:35], off
	v_addc_co_u32_e32 v45, vcc, -1, v23, vcc
	v_add_co_u32_e32 v34, vcc, 0xffffe000, v22
	v_add_co_u32_e64 v38, s[0:1], s9, v20
	s_nop 0
	v_addc_co_u32_e32 v35, vcc, -1, v23, vcc
	v_add_co_u32_e32 v42, vcc, 0xffffe200, v22
	global_load_dwordx2 v[100:101], v[44:45], off
	global_load_dwordx2 v[108:109], v[34:35], off
	v_addc_co_u32_e32 v43, vcc, -1, v23, vcc
	v_add_co_u32_e32 v34, vcc, 0xffffe400, v22
	v_addc_co_u32_e64 v39, s[0:1], 0, v21, s[0:1]
	s_nop 0
	v_addc_co_u32_e32 v35, vcc, -1, v23, vcc
	v_add_co_u32_e32 v44, vcc, 0xffffe600, v22
	global_load_dwordx2 v[120:121], v[42:43], off
	global_load_dwordx2 v[128:129], v[34:35], off
	v_addc_co_u32_e32 v45, vcc, -1, v23, vcc
	v_add_co_u32_e32 v34, vcc, 0xffffe800, v22
	s_waitcnt vmcnt(0) lgkmcnt(0)
	v_and_b32_e32 v53, 0xffff0000, v50
	v_addc_co_u32_e32 v35, vcc, -1, v23, vcc
	v_add_co_u32_e32 v42, vcc, 0xffffea00, v22
	global_load_dwordx2 v[132:133], v[44:45], off
	global_load_dwordx2 v[112:113], v[34:35], off
	v_addc_co_u32_e32 v43, vcc, -1, v23, vcc
	v_add_co_u32_e32 v34, vcc, 0xffffec00, v22
	v_and_b32_e32 v55, 0xffff0000, v51
	s_nop 0
	v_addc_co_u32_e32 v35, vcc, -1, v23, vcc
	v_add_co_u32_e32 v44, vcc, 0xffffee00, v22
	global_load_dwordx2 v[126:127], v[42:43], off
	global_load_dwordx2 v[130:131], v[34:35], off
	v_addc_co_u32_e32 v45, vcc, -1, v23, vcc
	v_add_co_u32_e32 v34, vcc, 0xfffff000, v22
	v_lshlrev_b32_e32 v52, 16, v50
	s_nop 0
	v_addc_co_u32_e32 v35, vcc, -1, v23, vcc
	v_add_co_u32_e32 v42, vcc, 0xfffff200, v22
	global_load_dwordx2 v[138:139], v[44:45], off
	global_load_dwordx2 v[118:119], v[34:35], off
	v_addc_co_u32_e32 v43, vcc, -1, v23, vcc
	v_add_co_u32_e32 v34, vcc, 0xfffff400, v22
	v_lshlrev_b32_e32 v54, 16, v51
	s_nop 0
	v_addc_co_u32_e32 v35, vcc, -1, v23, vcc
	v_add_co_u32_e32 v44, vcc, 0xfffff600, v22
	global_load_dwordx2 v[124:125], v[42:43], off
	global_load_dwordx2 v[134:135], v[34:35], off
	v_addc_co_u32_e32 v45, vcc, -1, v23, vcc
	v_add_co_u32_e32 v34, vcc, 0xfffff800, v22
	v_mul_f32_e32 v50, v55, v55
	s_nop 0
	v_addc_co_u32_e32 v35, vcc, -1, v23, vcc
	v_add_co_u32_e32 v42, vcc, 0xfffffa00, v22
	global_load_dwordx2 v[144:145], v[44:45], off
	global_load_dwordx2 v[154:155], v[34:35], off
	v_addc_co_u32_e32 v43, vcc, -1, v23, vcc
	v_add_co_u32_e32 v34, vcc, 0xfffffc00, v22
	global_load_dwordx2 v[160:161], v[42:43], off
	s_nop 0
	v_addc_co_u32_e32 v35, vcc, -1, v23, vcc
	v_add_co_u32_e32 v42, vcc, 0xfffffe00, v22
	v_and_b32_e32 v45, 0xffff0000, v48
	s_nop 0
	v_addc_co_u32_e32 v43, vcc, -1, v23, vcc
	global_load_dwordx2 v[156:157], v[34:35], off
	global_load_dwordx2 v[146:147], v[42:43], off
	global_load_dwordx2 v[140:141], v[22:23], off
	v_and_b32_e32 v35, 0xffff0000, v46
	v_and_b32_e32 v43, 0xffff0000, v47
	v_lshlrev_b32_e32 v34, 16, v46
	v_lshlrev_b32_e32 v42, 16, v47
	v_mul_f32_e32 v17, v35, v35
	v_mul_f32_e32 v19, v43, v43
	v_and_b32_e32 v47, 0xffff0000, v49
	v_lshlrev_b32_e32 v44, 16, v48
	v_lshlrev_b32_e32 v46, 16, v49
	v_fmac_f32_e32 v17, v34, v34
	v_fmac_f32_e32 v19, v42, v42
	v_mul_f32_e32 v48, v45, v45
	v_mul_f32_e32 v49, v47, v47
	v_add_f32_e32 v17, v17, v19
	v_fmac_f32_e32 v48, v44, v44
	v_fmac_f32_e32 v49, v46, v46
	v_mul_f32_e32 v19, v53, v53
	v_and_b32_e32 v61, 0xffff0000, v56
	v_and_b32_e32 v63, 0xffff0000, v57
	v_lshlrev_b32_e32 v60, 16, v56
	v_lshlrev_b32_e32 v62, 16, v57
; template <int M> __device__ __forceinline__ float swz_xor(float v) { static_assert(M >= 1 && M < 32, "swizzle xor mask"); return __int_as_float(__builtin_amdgcn_ds_swizzle(__float_as_int(v), (M << 10) | 0x1f)); }
; __device__ __forceinline__ float xor32_sum(float v) { auto r = __builtin_amdgcn_permlane32_swap(__float_as_uint(v), __float_as_uint(v), false, false); return __uint_as_float(r[0]) + __uint_as_float(r[1]); }
; __device__ __forceinline__ f32x4 unpack4(unsigned long long w) { const unsigned lo = (unsigned)w, hi = (unsigned)(w >> 32); return (f32x4){__uint_as_float(lo << 16), __uint_as_float(lo & 0xffff0000u), __uint_as_float(hi << 16), __uint_as_float(hi & 0xffff0000u)}; }
; __device__ __forceinline__ float wave_sum(float v) {
;     v += swz_xor<1>(v); v += swz_xor<2>(v); v += swz_xor<4>(v); v += swz_xor<8>(v); v += swz_xor<16>(v);
;     return xor32_sum(v);
; template <int MODE, int NR>
; __device__ __forceinline__ void norm_rows(const float* X32, bf16* X, bf16* H, float* out32, const f32x4 (&mul)[4], const f32x4 (&sh)[4], int lane) {
;     ...
;         for (int r = 0; r < NR; ++r) { f32x4 v[4]; float s = 0.f;
; #pragma unroll
;             for (int j = 0; j < 4; ++j) { v[j] = unpack4(raw[r][j]); s += (v[j].x * v[j].x + v[j].y * v[j].y) + (v[j].z * v[j].z + v[j].w * v[j].w); }
;             const float rstd = rsqrtf(wave_sum(s) * (1.f / D) + EPS);
	v_add_f32_e32 v48, v48, v49
	v_fmac_f32_e32 v19, v52, v52
	v_fmac_f32_e32 v50, v54, v54
	v_mul_f32_e32 v49, v61, v61
	v_mul_f32_e32 v51, v63, v63
	v_and_b32_e32 v69, 0xffff0000, v58
	v_and_b32_e32 v71, 0xffff0000, v59
	v_add_f32_e32 v17, v17, v48
	v_add_f32_e32 v19, v19, v50
	v_fmac_f32_e32 v49, v60, v60
	v_fmac_f32_e32 v51, v62, v62
	v_and_b32_e32 v81, 0xffff0000, v64
	v_and_b32_e32 v83, 0xffff0000, v65
	v_lshlrev_b32_e32 v68, 16, v58
	v_lshlrev_b32_e32 v70, 16, v59
	v_mul_f32_e32 v48, v69, v69
	v_mul_f32_e32 v50, v71, v71
	v_lshlrev_b32_e32 v80, 16, v64
	v_lshlrev_b32_e32 v82, 16, v65
	v_add_f32_e32 v17, v17, v19
	v_add_f32_e32 v19, v49, v51
	v_mul_f32_e32 v49, v81, v81
	v_mul_f32_e32 v51, v83, v83
	v_and_b32_e32 v93, 0xffff0000, v66
	v_and_b32_e32 v95, 0xffff0000, v67
	v_fmac_f32_e32 v48, v68, v68
	v_fmac_f32_e32 v50, v70, v70
	v_lshlrev_b32_e32 v92, 16, v66
	v_lshlrev_b32_e32 v94, 16, v67
	v_add_f32_e32 v17, v17, v19
	v_fmac_f32_e32 v49, v80, v80
	v_fmac_f32_e32 v51, v82, v82
	v_mul_f32_e32 v56, v93, v93
	v_mul_f32_e32 v57, v95, v95
	v_and_b32_e32 v105, 0xffff0000, v72
	v_and_b32_e32 v107, 0xffff0000, v73
	v_add_f32_e32 v19, v48, v50
	v_lshlrev_b32_e32 v104, 16, v72
	v_lshlrev_b32_e32 v106, 16, v73
	ds_swizzle_b32 v72, v17 offset:swizzle(SWAP,1)
	v_add_f32_e32 v58, v49, v51
	v_fmac_f32_e32 v56, v92, v92
	v_fmac_f32_e32 v57, v94, v94
	v_mul_f32_e32 v64, v105, v105
	v_mul_f32_e32 v65, v107, v107
	v_and_b32_e32 v49, 0xffff0000, v74
	v_and_b32_e32 v51, 0xffff0000, v75
	v_lshlrev_b32_e32 v48, 16, v74
	v_lshlrev_b32_e32 v50, 16, v75
	v_add_f32_e32 v19, v19, v58
	v_add_f32_e32 v66, v56, v57
	v_fmac_f32_e32 v64, v104, v104
	v_fmac_f32_e32 v65, v106, v106
	v_mul_f32_e32 v73, v49, v49
	v_mul_f32_e32 v74, v51, v51
	v_and_b32_e32 v57, 0xffff0000, v76
	v_and_b32_e32 v59, 0xffff0000, v77
	v_lshlrev_b32_e32 v56, 16, v76
	v_lshlrev_b32_e32 v58, 16, v77
	v_add_f32_e32 v19, v19, v66
	v_add_f32_e32 v75, v64, v65
	v_fmac_f32_e32 v73, v48, v48
	v_fmac_f32_e32 v74, v50, v50
	v_mul_f32_e32 v86, v57, v57
	v_mul_f32_e32 v87, v59, v59
	v_and_b32_e32 v65, 0xffff0000, v78
	v_and_b32_e32 v67, 0xffff0000, v79
	v_lshlrev_b32_e32 v64, 16, v78
	v_lshlrev_b32_e32 v66, 16, v79
	v_add_f32_e32 v19, v19, v75
	v_add_f32_e32 v73, v73, v74
	v_fmac_f32_e32 v86, v56, v56
	v_fmac_f32_e32 v87, v58, v58
	v_mul_f32_e32 v74, v65, v65
	v_mul_f32_e32 v75, v67, v67
	v_and_b32_e32 v77, 0xffff0000, v84
	v_and_b32_e32 v79, 0xffff0000, v85
	v_lshlrev_b32_e32 v76, 16, v84
	v_lshlrev_b32_e32 v78, 16, v85
	ds_swizzle_b32 v84, v19 offset:swizzle(SWAP,1)
	v_add_f32_e32 v85, v86, v87
	v_fmac_f32_e32 v74, v64, v64
	v_fmac_f32_e32 v75, v66, v66
	v_mul_f32_e32 v110, v77, v77
	v_mul_f32_e32 v111, v79, v79
	v_and_b32_e32 v87, 0xffff0000, v88
	v_and_b32_e32 v91, 0xffff0000, v89
	s_waitcnt lgkmcnt(0)
	v_add_f32_e32 v17, v17, v72
	v_add_f32_e32 v72, v73, v85
	v_add_f32_e32 v73, v74, v75
	v_fmac_f32_e32 v110, v76, v76
	v_fmac_f32_e32 v111, v78, v78
	v_and_b32_e32 v99, 0xffff0000, v96
	v_and_b32_e32 v103, 0xffff0000, v97
	v_lshlrev_b32_e32 v86, 16, v88
	v_lshlrev_b32_e32 v90, 16, v89
	v_mul_f32_e32 v74, v87, v87
	v_mul_f32_e32 v75, v91, v91
	v_lshlrev_b32_e32 v98, 16, v96
	v_lshlrev_b32_e32 v102, 16, v97
	ds_swizzle_b32 v136, v17 offset:swizzle(SWAP,2)
	v_add_f32_e32 v72, v72, v73
	v_add_f32_e32 v73, v110, v111
	v_mul_f32_e32 v85, v99, v99
	v_mul_f32_e32 v88, v103, v103
	v_and_b32_e32 v111, 0xffff0000, v100
	v_and_b32_e32 v115, 0xffff0000, v101
	v_fmac_f32_e32 v74, v86, v86
	v_fmac_f32_e32 v75, v90, v90
	v_lshlrev_b32_e32 v110, 16, v100
	v_lshlrev_b32_e32 v114, 16, v101
	v_add_f32_e32 v137, v72, v73
	v_fmac_f32_e32 v85, v98, v98
	v_fmac_f32_e32 v88, v102, v102
	v_mul_f32_e32 v96, v111, v111
	v_mul_f32_e32 v97, v115, v115
	v_and_b32_e32 v117, 0xffff0000, v108
	v_and_b32_e32 v123, 0xffff0000, v109
	v_add_f32_e32 v89, v74, v75
	v_lshlrev_b32_e32 v116, 16, v108
	v_lshlrev_b32_e32 v122, 16, v109
	ds_swizzle_b32 v142, v137 offset:swizzle(SWAP,1)
	v_add_f32_e32 v85, v85, v88
	v_fmac_f32_e32 v96, v110, v110
	v_fmac_f32_e32 v97, v114, v114
	v_mul_f32_e32 v100, v117, v117
	v_mul_f32_e32 v101, v123, v123
	v_and_b32_e32 v73, 0xffff0000, v120
	v_and_b32_e32 v75, 0xffff0000, v121
	v_lshlrev_b32_e32 v72, 16, v120
	v_lshlrev_b32_e32 v74, 16, v121
	v_add_f32_e32 v19, v19, v84
	v_add_f32_e32 v108, v89, v85
	v_add_f32_e32 v96, v96, v97
	v_fmac_f32_e32 v100, v116, v116
	v_fmac_f32_e32 v101, v122, v122
	v_mul_f32_e32 v109, v73, v73
	v_mul_f32_e32 v120, v75, v75
	v_and_b32_e32 v85, 0xffff0000, v128
	v_and_b32_e32 v89, 0xffff0000, v129
	v_lshlrev_b32_e32 v84, 16, v128
	v_lshlrev_b32_e32 v88, 16, v129
	ds_swizzle_b32 v143, v19 offset:swizzle(SWAP,2)
	v_add_f32_e32 v108, v108, v96
	v_add_f32_e32 v121, v100, v101
	v_fmac_f32_e32 v109, v72, v72
	v_fmac_f32_e32 v120, v74, v74
	v_mul_f32_e32 v128, v85, v85
	v_mul_f32_e32 v129, v89, v89
	s_waitcnt vmcnt(0)
	v_and_b32_e32 v97, 0xffff0000, v132
	v_and_b32_e32 v101, 0xffff0000, v133
	v_lshlrev_b32_e32 v96, 16, v132
	v_lshlrev_b32_e32 v100, 16, v133
	s_waitcnt lgkmcnt(2)
	v_add_f32_e32 v17, v17, v136
	v_add_f32_e32 v152, v108, v121
	v_add_f32_e32 v132, v109, v120
	v_fmac_f32_e32 v128, v84, v84
	v_fmac_f32_e32 v129, v88, v88
	v_mul_f32_e32 v133, v97, v97
	v_mul_f32_e32 v136, v101, v101
	v_lshlrev_b32_e32 v108, 16, v112
	v_and_b32_e32 v109, 0xffff0000, v112
	v_lshlrev_b32_e32 v112, 16, v113
	v_and_b32_e32 v113, 0xffff0000, v113
	ds_swizzle_b32 v153, v17 offset:swizzle(SWAP,4)
	ds_swizzle_b32 v158, v152 offset:swizzle(SWAP,1)
	v_add_f32_e32 v128, v128, v129
	v_fmac_f32_e32 v133, v96, v96
	v_fmac_f32_e32 v136, v100, v100
	v_mul_f32_e32 v148, v109, v109
	v_mul_f32_e32 v149, v113, v113
	v_lshlrev_b32_e32 v120, 16, v126
	v_and_b32_e32 v121, 0xffff0000, v126
	v_lshlrev_b32_e32 v126, 16, v127
	v_and_b32_e32 v127, 0xffff0000, v127
	s_waitcnt lgkmcnt(3)
; template <int M> __device__ __forceinline__ float swz_xor(float v) { static_assert(M >= 1 && M < 32, "swizzle xor mask"); return __int_as_float(__builtin_amdgcn_ds_swizzle(__float_as_int(v), (M << 10) | 0x1f)); }
; __device__ __forceinline__ float xor32_sum(float v) { auto r = __builtin_amdgcn_permlane32_swap(__float_as_uint(v), __float_as_uint(v), false, false); return __uint_as_float(r[0]) + __uint_as_float(r[1]); }
; __device__ __forceinline__ f32x4 unpack4(unsigned long long w) { const unsigned lo = (unsigned)w, hi = (unsigned)(w >> 32); return (f32x4){__uint_as_float(lo << 16), __uint_as_float(lo & 0xffff0000u), __uint_as_float(hi << 16), __uint_as_float(hi & 0xffff0000u)}; }
; __device__ __forceinline__ float wave_sum(float v) {
;     v += swz_xor<1>(v); v += swz_xor<2>(v); v += swz_xor<4>(v); v += swz_xor<8>(v); v += swz_xor<16>(v);
;     return xor32_sum(v);
; template <int MODE, int NR>
; __device__ __forceinline__ void norm_rows(const float* X32, bf16* X, bf16* H, float* out32, const f32x4 (&mul)[4], const f32x4 (&sh)[4], int lane) {
;     ...
;         for (int r = 0; r < NR; ++r) { f32x4 v[4]; float s = 0.f;
; #pragma unroll
;             for (int j = 0; j < 4; ++j) { v[j] = unpack4(raw[r][j]); s += (v[j].x * v[j].x + v[j].y * v[j].y) + (v[j].z * v[j].z + v[j].w * v[j].w); }
;             const float rstd = rsqrtf(wave_sum(s) * (1.f / D) + EPS);
	v_add_f32_e32 v159, v137, v142
	v_add_f32_e32 v137, v132, v128
	v_add_f32_e32 v136, v133, v136
	v_fmac_f32_e32 v148, v108, v108
	v_fmac_f32_e32 v149, v112, v112
	v_mul_f32_e32 v142, v121, v121
	v_mul_f32_e32 v150, v127, v127
	v_and_b32_e32 v129, 0xffff0000, v130
	v_and_b32_e32 v133, 0xffff0000, v131
	v_lshlrev_b32_e32 v128, 16, v130
	v_lshlrev_b32_e32 v132, 16, v131
	ds_swizzle_b32 v162, v159 offset:swizzle(SWAP,2)
	v_add_f32_e32 v130, v137, v136
	v_add_f32_e32 v131, v148, v149
	v_fmac_f32_e32 v142, v120, v120
	v_fmac_f32_e32 v150, v126, v126
	v_mul_f32_e32 v163, v129, v129
	v_mul_f32_e32 v164, v133, v133
	v_lshlrev_b32_e32 v136, 16, v138
	v_and_b32_e32 v137, 0xffff0000, v138
	v_lshlrev_b32_e32 v138, 16, v139
	v_and_b32_e32 v139, 0xffff0000, v139
	s_waitcnt lgkmcnt(3)
	v_add_f32_e32 v19, v19, v143
	v_add_f32_e32 v165, v130, v131
	v_add_f32_e32 v130, v142, v150
	v_fmac_f32_e32 v163, v128, v128
	v_fmac_f32_e32 v164, v132, v132
	v_mul_f32_e32 v131, v137, v137
	v_mul_f32_e32 v142, v139, v139
	v_and_b32_e32 v149, 0xffff0000, v118
	v_and_b32_e32 v151, 0xffff0000, v119
	v_lshlrev_b32_e32 v148, 16, v118
	v_lshlrev_b32_e32 v150, 16, v119
	ds_swizzle_b32 v166, v19 offset:swizzle(SWAP,4)
	ds_swizzle_b32 v167, v165 offset:swizzle(SWAP,1)
	v_add_f32_e32 v143, v163, v164
	v_fmac_f32_e32 v131, v136, v136
	v_fmac_f32_e32 v142, v138, v138
	v_mul_f32_e32 v163, v149, v149
	v_mul_f32_e32 v164, v151, v151
	v_lshlrev_b32_e32 v118, 16, v124
	v_and_b32_e32 v119, 0xffff0000, v124
	v_lshlrev_b32_e32 v124, 16, v125
	v_and_b32_e32 v125, 0xffff0000, v125
	s_waitcnt lgkmcnt(4)
	v_add_f32_e32 v17, v17, v153
	s_waitcnt lgkmcnt(3)
	v_add_f32_e32 v168, v152, v158
	v_add_f32_e32 v143, v130, v143
	v_add_f32_e32 v142, v131, v142
	v_fmac_f32_e32 v163, v148, v148
	v_fmac_f32_e32 v164, v150, v150
	v_mul_f32_e32 v152, v119, v119
	v_mul_f32_e32 v153, v125, v125
	v_lshlrev_b32_e32 v130, 16, v134
	v_and_b32_e32 v131, 0xffff0000, v134
	v_lshlrev_b32_e32 v134, 16, v135
	v_and_b32_e32 v135, 0xffff0000, v135
	ds_swizzle_b32 v169, v17 offset:swizzle(SWAP,8)
	ds_swizzle_b32 v170, v168 offset:swizzle(SWAP,2)
	v_add_f32_e32 v158, v143, v142
	v_add_f32_e32 v163, v163, v164
	v_fmac_f32_e32 v152, v118, v118
	v_fmac_f32_e32 v153, v124, v124
	v_mul_f32_e32 v164, v131, v131
	v_mul_f32_e32 v171, v135, v135
	v_lshlrev_b32_e32 v142, 16, v144
	v_and_b32_e32 v143, 0xffff0000, v144
	v_lshlrev_b32_e32 v144, 16, v145
	v_and_b32_e32 v145, 0xffff0000, v145
	s_waitcnt lgkmcnt(4)
	v_add_f32_e32 v172, v159, v162
	v_add_f32_e32 v173, v158, v163
	v_add_f32_e32 v162, v152, v153
	v_fmac_f32_e32 v164, v130, v130
	v_fmac_f32_e32 v171, v134, v134
	v_mul_f32_e32 v163, v143, v143
	v_mul_f32_e32 v174, v145, v145
	v_lshlrev_b32_e32 v152, 16, v154
	v_and_b32_e32 v153, 0xffff0000, v154
	v_lshlrev_b32_e32 v154, 16, v155
	v_and_b32_e32 v155, 0xffff0000, v155
	v_add_f32_e32 v164, v164, v171
	v_fmac_f32_e32 v163, v142, v142
	v_fmac_f32_e32 v174, v144, v144
	v_mul_f32_e32 v171, v153, v153
	v_mul_f32_e32 v177, v155, v155
	v_lshlrev_b32_e32 v158, 16, v160
	v_and_b32_e32 v159, 0xffff0000, v160
	v_lshlrev_b32_e32 v160, 16, v161
	v_and_b32_e32 v161, 0xffff0000, v161
	ds_swizzle_b32 v175, v172 offset:swizzle(SWAP,4)
	ds_swizzle_b32 v176, v173 offset:swizzle(SWAP,1)
	s_waitcnt lgkmcnt(5)
	v_add_f32_e32 v19, v19, v166
	s_waitcnt lgkmcnt(4)
	v_add_f32_e32 v178, v165, v167
	v_add_f32_e32 v164, v162, v164
	v_add_f32_e32 v165, v163, v174
	v_fmac_f32_e32 v171, v152, v152
	v_fmac_f32_e32 v177, v154, v154
	v_mul_f32_e32 v174, v159, v159
	v_mul_f32_e32 v179, v161, v161
	v_lshlrev_b32_e32 v162, 16, v156
	v_and_b32_e32 v163, 0xffff0000, v156
	v_lshlrev_b32_e32 v156, 16, v157
	v_and_b32_e32 v157, 0xffff0000, v157
	ds_swizzle_b32 v180, v19 offset:swizzle(SWAP,8)
	ds_swizzle_b32 v181, v178 offset:swizzle(SWAP,2)
	v_add_f32_e32 v182, v164, v165
	v_add_f32_e32 v171, v171, v177
	v_fmac_f32_e32 v174, v158, v158
	v_fmac_f32_e32 v179, v160, v160
	v_mul_f32_e32 v177, v163, v163
	v_mul_f32_e32 v183, v157, v157
	v_lshlrev_b32_e32 v164, 16, v146
	v_and_b32_e32 v165, 0xffff0000, v146
	v_lshlrev_b32_e32 v146, 16, v147
	v_and_b32_e32 v147, 0xffff0000, v147
	v_lshlrev_b32_e32 v166, 16, v140
	v_and_b32_e32 v167, 0xffff0000, v140
	v_lshlrev_b32_e32 v140, 16, v141
	v_and_b32_e32 v141, 0xffff0000, v141
	s_waitcnt lgkmcnt(5)
	v_add_f32_e32 v17, v17, v169
	s_waitcnt lgkmcnt(4)
	v_add_f32_e32 v168, v168, v170
	v_add_f32_e32 v170, v182, v171
	v_add_f32_e32 v169, v174, v179
	v_fmac_f32_e32 v177, v162, v162
	v_fmac_f32_e32 v183, v156, v156
	v_mul_f32_e32 v171, v165, v165
	v_mul_f32_e32 v174, v147, v147
	v_mul_f32_e32 v179, v167, v167
	v_mul_f32_e32 v182, v141, v141
	v_add_f32_e32 v177, v177, v183
	v_fmac_f32_e32 v171, v164, v164
	v_fmac_f32_e32 v174, v146, v146
	ds_swizzle_b32 v184, v17 offset:swizzle(SWAP,16)
	ds_swizzle_b32 v185, v168 offset:swizzle(SWAP,4)
	v_fmac_f32_e32 v179, v166, v166
	v_fmac_f32_e32 v182, v140, v140
	v_add_f32_e32 v169, v169, v177
	v_add_f32_e32 v171, v171, v174
	ds_swizzle_b32 v186, v170 offset:swizzle(SWAP,1)
	s_waitcnt lgkmcnt(6)
	v_add_f32_e32 v172, v172, v175
	s_waitcnt lgkmcnt(5)
	v_add_f32_e32 v173, v173, v176
	v_add_f32_e32 v174, v179, v182
	v_add_f32_e32 v169, v169, v171
	ds_swizzle_b32 v175, v172 offset:swizzle(SWAP,8)
	ds_swizzle_b32 v176, v173 offset:swizzle(SWAP,2)
	s_waitcnt lgkmcnt(6)
	v_add_f32_e32 v19, v19, v180
	s_waitcnt lgkmcnt(5)
	v_add_f32_e32 v177, v178, v181
	v_add_f32_e32 v174, v169, v174
	ds_swizzle_b32 v178, v19 offset:swizzle(SWAP,16)
	ds_swizzle_b32 v179, v177 offset:swizzle(SWAP,4)
	ds_swizzle_b32 v180, v174 offset:swizzle(SWAP,1)
	s_waitcnt lgkmcnt(7)
	v_add_f32_e32 v169, v17, v184
	s_waitcnt lgkmcnt(6)
; template <int MODE, int NR>
; __device__ __forceinline__ void norm_rows(const float* X32, bf16* X, bf16* H, float* out32, const f32x4 (&mul)[4], const f32x4 (&sh)[4], int lane) {
;     ...
;             const float rstd = rsqrtf(wave_sum(s) * (1.f / D) + EPS);
;             if constexpr (MODE == 2) { f32x4* o = (f32x4*)(out32 + (size_t)r * D) + lane;
; #pragma unroll
;                 for (int j = 0; j < 4; ++j) o[64 * j] = v[j] * rstd * mul[j];
	v_add_f32_e32 v17, v168, v185
	s_waitcnt lgkmcnt(5)
	v_add_f32_e32 v181, v170, v186
	ds_swizzle_b32 v182, v17 offset:swizzle(SWAP,8)
	ds_swizzle_b32 v183, v181 offset:swizzle(SWAP,2)
	s_waitcnt lgkmcnt(6)
	v_add_f32_e32 v172, v172, v175
	s_waitcnt lgkmcnt(5)
	v_add_f32_e32 v173, v173, v176
	ds_swizzle_b32 v175, v172 offset:swizzle(SWAP,16)
	ds_swizzle_b32 v176, v173 offset:swizzle(SWAP,4)
	s_waitcnt lgkmcnt(6)
	v_add_f32_e32 v168, v19, v178
	s_waitcnt lgkmcnt(5)
	v_add_f32_e32 v19, v177, v179
	s_waitcnt lgkmcnt(4)
	v_add_f32_e32 v174, v174, v180
	v_mov_b32_e32 v171, v169
	v_mov_b32_e32 v170, v168
	ds_swizzle_b32 v177, v19 offset:swizzle(SWAP,8)
	ds_swizzle_b32 v178, v174 offset:swizzle(SWAP,2)
	v_permlane32_swap_b32_e32 v169, v171
	v_permlane32_swap_b32_e32 v168, v170
	v_add_co_u32_e64 v36, s[0:1], s10, v20
	s_waitcnt lgkmcnt(5)
	v_add_f32_e32 v17, v17, v182
	v_pk_add_f32 v[168:169], v[168:169], v[170:171]
	v_addc_co_u32_e64 v37, s[0:1], 0, v21, s[0:1]
	s_waitcnt lgkmcnt(4)
	v_add_f32_e32 v179, v181, v183
	ds_swizzle_b32 v170, v17 offset:swizzle(SWAP,16)
	v_pk_fma_f32 v[168:169], v[168:169], s[4:5], v[24:25] op_sel_hi:[1,0,0]
	v_add_co_u32_e64 v40, s[0:1], s11, v20
	ds_swizzle_b32 v180, v179 offset:swizzle(SWAP,4)
	s_waitcnt lgkmcnt(5)
	v_add_f32_e32 v171, v172, v175
	s_waitcnt lgkmcnt(4)
	v_add_f32_e32 v175, v173, v176
	v_mul_f32_e32 v176, 0x4b800000, v168
	v_cmp_gt_f32_e32 vcc, s3, v168
	v_addc_co_u32_e64 v41, s[0:1], 0, v21, s[0:1]
	ds_swizzle_b32 v181, v175 offset:swizzle(SWAP,8)
	v_cndmask_b32_e32 v168, v168, v176, vcc
	s_waitcnt lgkmcnt(4)
	v_add_f32_e32 v19, v19, v177
	s_waitcnt lgkmcnt(3)
	v_add_f32_e32 v176, v174, v178
	v_mul_f32_e32 v172, 0x4b800000, v169
	v_cmp_gt_f32_e64 s[0:1], s3, v169
	ds_swizzle_b32 v178, v19 offset:swizzle(SWAP,16)
	ds_swizzle_b32 v182, v176 offset:swizzle(SWAP,4)
	v_cndmask_b32_e64 v169, v169, v172, s[0:1]
	v_rsq_f32_e32 v174, v169
	v_rsq_f32_e32 v177, v168
	s_waitcnt lgkmcnt(4)
	v_add_f32_e32 v170, v17, v170
	v_mov_b32_e32 v173, v171
	s_waitcnt lgkmcnt(3)
	v_add_f32_e32 v17, v179, v180
	v_mov_b32_e32 v172, v170
	v_permlane32_swap_b32_e32 v171, v173
	ds_swizzle_b32 v198, v17 offset:swizzle(SWAP,8)
	v_permlane32_swap_b32_e32 v170, v172
	s_waitcnt lgkmcnt(3)
	v_add_f32_e32 v200, v175, v181
	v_pk_add_f32 v[168:169], v[170:171], v[172:173]
	ds_swizzle_b32 v201, v200 offset:swizzle(SWAP,16)
	s_waitcnt lgkmcnt(3)
	v_add_f32_e32 v173, v19, v178
	s_waitcnt lgkmcnt(2)
	v_add_f32_e32 v19, v176, v182
	v_mul_f32_e32 v175, 0x45800000, v174
	v_mul_f32_e32 v179, 0x45800000, v177
	ds_swizzle_b32 v203, v19 offset:swizzle(SWAP,8)
	v_cndmask_b32_e64 v170, v174, v175, s[0:1]
	v_cndmask_b32_e32 v172, v177, v179, vcc
	v_pk_fma_f32 v[174:175], v[168:169], s[4:5], v[24:25] op_sel_hi:[1,0,0]
	v_pk_mul_f32 v[34:35], v[34:35], v[170:171] op_sel_hi:[1,0]
	v_pk_mul_f32 v[42:43], v[42:43], v[170:171] op_sel_hi:[1,0]
	v_pk_mul_f32 v[182:183], v[68:69], v[172:173] op_sel_hi:[1,0]
	v_pk_mul_f32 v[184:185], v[70:71], v[172:173] op_sel_hi:[1,0]
	v_pk_mul_f32 v[186:187], v[80:81], v[172:173] op_sel_hi:[1,0]
	v_pk_mul_f32 v[188:189], v[82:83], v[172:173] op_sel_hi:[1,0]
	v_pk_mul_f32 v[190:191], v[92:93], v[172:173] op_sel_hi:[1,0]
	v_pk_mul_f32 v[192:193], v[94:95], v[172:173] op_sel_hi:[1,0]
	v_pk_mul_f32 v[194:195], v[104:105], v[172:173] op_sel_hi:[1,0]
	v_pk_mul_f32 v[196:197], v[106:107], v[172:173] op_sel_hi:[1,0]
	v_mul_f32_e32 v172, 0x4b800000, v175
	v_mul_f32_e32 v202, 0x4b800000, v174
	v_cmp_gt_f32_e32 vcc, s3, v174
	v_cmp_gt_f32_e64 s[0:1], s3, v175
	v_pk_mul_f32 v[168:169], v[44:45], v[170:171] op_sel_hi:[1,0]
	v_pk_mul_f32 v[46:47], v[46:47], v[170:171] op_sel_hi:[1,0]
	v_pk_mul_f32 v[176:177], v[52:53], v[170:171] op_sel_hi:[1,0]
	v_pk_mul_f32 v[178:179], v[54:55], v[170:171] op_sel_hi:[1,0]
	v_pk_mul_f32 v[180:181], v[60:61], v[170:171] op_sel_hi:[1,0]
	v_pk_mul_f32 v[170:171], v[62:63], v[170:171] op_sel_hi:[1,0]
	v_pk_mul_f32 v[44:45], v[2:3], v[42:43]
	v_pk_mul_f32 v[42:43], v[0:1], v[34:35]
	v_cndmask_b32_e64 v34, v175, v172, s[0:1]
	v_cndmask_b32_e32 v35, v174, v202, vcc
	s_waitcnt lgkmcnt(2)
	v_add_f32_e32 v17, v17, v198
	v_pk_mul_f32 v[54:55], v[6:7], v[46:47]
	v_pk_mul_f32 v[52:53], v[4:5], v[168:169]
	v_pk_mul_f32 v[62:63], v[10:11], v[178:179]
	v_pk_mul_f32 v[60:61], v[8:9], v[176:177]
	v_pk_mul_f32 v[70:71], v[14:15], v[170:171]
	v_pk_mul_f32 v[68:69], v[12:13], v[180:181]
	v_pk_mul_f32 v[82:83], v[2:3], v[184:185]
	v_pk_mul_f32 v[80:81], v[0:1], v[182:183]
	v_pk_mul_f32 v[94:95], v[6:7], v[188:189]
	v_pk_mul_f32 v[92:93], v[4:5], v[186:187]
	v_pk_mul_f32 v[106:107], v[10:11], v[192:193]
	v_pk_mul_f32 v[104:105], v[8:9], v[190:191]
	v_pk_mul_f32 v[170:171], v[14:15], v[196:197]
	v_pk_mul_f32 v[168:169], v[12:13], v[194:195]
	global_store_dwordx4 v[20:21], v[42:45], off nt
	global_store_dwordx4 v[20:21], v[52:55], off offset:1024 nt
	global_store_dwordx4 v[20:21], v[60:63], off offset:2048 nt
	global_store_dwordx4 v[20:21], v[68:71], off offset:3072 nt
	global_store_dwordx4 v[26:27], v[80:83], off offset:-4096 nt
	global_store_dwordx4 v[28:29], v[92:95], off offset:1024 nt
	global_store_dwordx4 v[28:29], v[104:107], off offset:2048 nt
	global_store_dwordx4 v[28:29], v[168:171], off offset:3072 nt
	v_rsq_f32_e32 v34, v34
	v_rsq_f32_e32 v35, v35
	ds_swizzle_b32 v43, v17 offset:swizzle(SWAP,16)
	s_waitcnt lgkmcnt(2)
	v_add_f32_e32 v172, v200, v201
	v_mov_b32_e32 v199, v173
	v_mov_b32_e32 v198, v172
	s_waitcnt lgkmcnt(1)
; template <int MODE, int NR>
; __device__ __forceinline__ void norm_rows(const float* X32, bf16* X, bf16* H, float* out32, const f32x4 (&mul)[4], const f32x4 (&sh)[4], int lane) {
;     ...
;             const float rstd = rsqrtf(wave_sum(s) * (1.f / D) + EPS);
;             if constexpr (MODE == 2) { f32x4* o = (f32x4*)(out32 + (size_t)r * D) + lane;
; #pragma unroll
;                 for (int j = 0; j < 4; ++j) o[64 * j] = v[j] * rstd * mul[j];
	v_add_f32_e32 v19, v19, v203
	v_permlane32_swap_b32_e32 v173, v199
	v_permlane32_swap_b32_e32 v172, v198
	ds_swizzle_b32 v80, v19 offset:swizzle(SWAP,16)
	v_pk_add_f32 v[28:29], v[172:173], v[198:199]
	v_mul_f32_e32 v42, 0x45800000, v34
	v_mul_f32_e32 v44, 0x45800000, v35
	v_pk_fma_f32 v[28:29], v[28:29], s[4:5], v[24:25] op_sel_hi:[1,0,0]
	v_cndmask_b32_e64 v34, v34, v42, s[0:1]
	v_cndmask_b32_e32 v42, v35, v44, vcc
	s_waitcnt lgkmcnt(1)
	v_add_f32_e32 v35, v17, v43
	v_mul_f32_e32 v17, 0x4b800000, v29
	v_cmp_gt_f32_e64 s[0:1], s3, v29
	v_pk_mul_f32 v[46:47], v[48:49], v[34:35] op_sel_hi:[1,0]
	v_pk_mul_f32 v[44:45], v[50:51], v[34:35] op_sel_hi:[1,0]
	v_pk_mul_f32 v[50:51], v[56:57], v[34:35] op_sel_hi:[1,0]
	v_pk_mul_f32 v[48:49], v[58:59], v[34:35] op_sel_hi:[1,0]
	v_pk_mul_f32 v[54:55], v[64:65], v[34:35] op_sel_hi:[1,0]
	v_pk_mul_f32 v[52:53], v[66:67], v[34:35] op_sel_hi:[1,0]
	v_pk_mul_f32 v[58:59], v[76:77], v[34:35] op_sel_hi:[1,0]
	v_pk_mul_f32 v[56:57], v[78:79], v[34:35] op_sel_hi:[1,0]
	v_mul_f32_e32 v34, 0x4b800000, v28
	v_cmp_gt_f32_e32 vcc, s3, v28
	v_cndmask_b32_e64 v17, v29, v17, s[0:1]
	v_rsq_f32_e32 v17, v17
	v_cndmask_b32_e32 v28, v28, v34, vcc
	s_waitcnt lgkmcnt(0)
; template <int MODE, int NR>
; __device__ __forceinline__ void norm_rows(const float* X32, bf16* X, bf16* H, float* out32, const f32x4 (&mul)[4], const f32x4 (&sh)[4], int lane) {
;     ...
;             const float rstd = rsqrtf(wave_sum(s) * (1.f / D) + EPS);
;             if constexpr (MODE == 2) { f32x4* o = (f32x4*)(out32 + (size_t)r * D) + lane;
; #pragma unroll
;                 for (int j = 0; j < 4; ++j) o[64 * j] = v[j] * rstd * mul[j];
	v_add_f32_e32 v34, v19, v80
	v_mov_b32_e32 v81, v35
	v_rsq_f32_e32 v29, v28
	v_mov_b32_e32 v80, v34
	v_pk_mul_f32 v[62:63], v[86:87], v[42:43] op_sel_hi:[1,0]
	v_pk_mul_f32 v[60:61], v[90:91], v[42:43] op_sel_hi:[1,0]
	v_pk_mul_f32 v[66:67], v[98:99], v[42:43] op_sel_hi:[1,0]
	v_pk_mul_f32 v[64:65], v[102:103], v[42:43] op_sel_hi:[1,0]
	v_pk_mul_f32 v[70:71], v[110:111], v[42:43] op_sel_hi:[1,0]
	v_pk_mul_f32 v[68:69], v[114:115], v[42:43] op_sel_hi:[1,0]
	v_pk_mul_f32 v[76:77], v[116:117], v[42:43] op_sel_hi:[1,0]
	v_pk_mul_f32 v[78:79], v[122:123], v[42:43] op_sel_hi:[1,0]
	v_pk_mul_f32 v[44:45], v[2:3], v[44:45]
	v_pk_mul_f32 v[42:43], v[0:1], v[46:47]
	v_permlane32_swap_b32_e32 v35, v81
	v_permlane32_swap_b32_e32 v34, v80
	v_pk_mul_f32 v[48:49], v[6:7], v[48:49]
	v_pk_mul_f32 v[46:47], v[4:5], v[50:51]
	v_pk_mul_f32 v[52:53], v[10:11], v[52:53]
	v_pk_mul_f32 v[50:51], v[8:9], v[54:55]
	v_pk_mul_f32 v[56:57], v[14:15], v[56:57]
	v_pk_mul_f32 v[54:55], v[12:13], v[58:59]
	v_pk_mul_f32 v[60:61], v[2:3], v[60:61]
	v_pk_mul_f32 v[58:59], v[0:1], v[62:63]
	v_pk_mul_f32 v[64:65], v[6:7], v[64:65]
	v_pk_mul_f32 v[62:63], v[4:5], v[66:67]
	v_pk_mul_f32 v[68:69], v[10:11], v[68:69]
	v_pk_mul_f32 v[66:67], v[8:9], v[70:71]
	v_pk_mul_f32 v[78:79], v[14:15], v[78:79]
	v_pk_mul_f32 v[76:77], v[12:13], v[76:77]
	global_store_dwordx4 v[26:27], v[42:45], off nt
	global_store_dwordx4 v[26:27], v[46:49], off offset:1024 nt
	global_store_dwordx4 v[26:27], v[50:53], off offset:2048 nt
	global_store_dwordx4 v[26:27], v[54:57], off offset:3072 nt
	global_store_dwordx4 v[30:31], v[58:61], off offset:-4096 nt
	global_store_dwordx4 v[32:33], v[62:65], off offset:1024 nt
	global_store_dwordx4 v[32:33], v[66:69], off offset:2048 nt
	global_store_dwordx4 v[32:33], v[76:79], off offset:3072 nt
	v_pk_add_f32 v[26:27], v[34:35], v[80:81]
	v_mul_f32_e32 v19, 0x45800000, v17
	v_pk_fma_f32 v[66:67], v[26:27], s[4:5], v[24:25] op_sel_hi:[1,0,0]
	v_mul_f32_e32 v32, 0x45800000, v29
	v_cndmask_b32_e64 v28, v17, v19, s[0:1]
	v_mul_f32_e32 v17, 0x4b800000, v67
	v_cmp_gt_f32_e64 s[0:1], s3, v67
	v_cndmask_b32_e32 v32, v29, v32, vcc
	v_mul_f32_e32 v19, 0x4b800000, v66
	v_cmp_gt_f32_e32 vcc, s3, v66
	v_cndmask_b32_e64 v17, v67, v17, s[0:1]
	v_rsq_f32_e32 v17, v17
	v_cndmask_b32_e32 v19, v66, v19, vcc
	v_rsq_f32_e32 v19, v19
	v_pk_mul_f32 v[26:27], v[72:73], v[28:29] op_sel_hi:[1,0]
	v_pk_mul_f32 v[34:35], v[74:75], v[28:29] op_sel_hi:[1,0]
	v_pk_mul_f32 v[42:43], v[84:85], v[28:29] op_sel_hi:[1,0]
	v_pk_mul_f32 v[44:45], v[88:89], v[28:29] op_sel_hi:[1,0]
	v_pk_mul_f32 v[46:47], v[96:97], v[28:29] op_sel_hi:[1,0]
	v_pk_mul_f32 v[48:49], v[100:101], v[28:29] op_sel_hi:[1,0]
	v_pk_mul_f32 v[50:51], v[108:109], v[28:29] op_sel_hi:[1,0]
	v_pk_mul_f32 v[52:53], v[112:113], v[28:29] op_sel_hi:[1,0]
	v_pk_mul_f32 v[54:55], v[120:121], v[32:33] op_sel_hi:[1,0]
	v_pk_mul_f32 v[56:57], v[126:127], v[32:33] op_sel_hi:[1,0]
	v_pk_mul_f32 v[58:59], v[128:129], v[32:33] op_sel_hi:[1,0]
	v_pk_mul_f32 v[60:61], v[132:133], v[32:33] op_sel_hi:[1,0]
	v_pk_mul_f32 v[28:29], v[2:3], v[34:35]
	v_pk_mul_f32 v[26:27], v[0:1], v[26:27]
	v_pk_mul_f32 v[62:63], v[136:137], v[32:33] op_sel_hi:[1,0]
	v_pk_mul_f32 v[64:65], v[138:139], v[32:33] op_sel_hi:[1,0]
	v_pk_mul_f32 v[68:69], v[148:149], v[32:33] op_sel_hi:[1,0]
	v_pk_mul_f32 v[70:71], v[150:151], v[32:33] op_sel_hi:[1,0]
	v_pk_mul_f32 v[34:35], v[6:7], v[44:45]
	v_pk_mul_f32 v[32:33], v[4:5], v[42:43]
	v_pk_mul_f32 v[44:45], v[10:11], v[48:49]
	v_pk_mul_f32 v[42:43], v[8:9], v[46:47]
	v_pk_mul_f32 v[48:49], v[14:15], v[52:53]
	v_pk_mul_f32 v[46:47], v[12:13], v[50:51]
	v_pk_mul_f32 v[52:53], v[2:3], v[56:57]
	v_pk_mul_f32 v[50:51], v[0:1], v[54:55]
	v_pk_mul_f32 v[56:57], v[6:7], v[60:61]
	v_pk_mul_f32 v[54:55], v[4:5], v[58:59]
	global_store_dwordx4 v[30:31], v[26:29], off nt
	global_store_dwordx4 v[30:31], v[32:35], off offset:1024 nt
	global_store_dwordx4 v[30:31], v[42:45], off offset:2048 nt
	global_store_dwordx4 v[30:31], v[46:49], off offset:3072 nt
	global_store_dwordx4 v[36:37], v[50:53], off offset:-4096 nt
	global_store_dwordx4 v[38:39], v[54:57], off offset:1024 nt
	v_mul_f32_e32 v26, 0x45800000, v17
	v_mul_f32_e32 v27, 0x45800000, v19
	v_cndmask_b32_e64 v26, v17, v26, s[0:1]
	s_add_i32 s12, s12, s96
	v_pk_mul_f32 v[60:61], v[10:11], v[64:65]
	v_pk_mul_f32 v[58:59], v[8:9], v[62:63]
	v_pk_mul_f32 v[64:65], v[14:15], v[70:71]
	v_pk_mul_f32 v[62:63], v[12:13], v[68:69]
	v_cndmask_b32_e32 v28, v19, v27, vcc
	v_pk_mul_f32 v[30:31], v[118:119], v[26:27] op_sel_hi:[1,0]
	v_pk_mul_f32 v[32:33], v[124:125], v[26:27] op_sel_hi:[1,0]
	s_cmpk_gt_i32 s12, 0x7ff
	v_lshl_add_u64 v[22:23], v[22:23], 0, s[78:79]
	v_lshl_add_u64 v[20:21], v[20:21], 0, s[16:17]
	global_store_dwordx4 v[38:39], v[58:61], off offset:2048 nt
	global_store_dwordx4 v[38:39], v[62:65], off offset:3072 nt
	v_pk_mul_f32 v[34:35], v[130:131], v[26:27] op_sel_hi:[1,0]
	v_pk_mul_f32 v[38:39], v[134:135], v[26:27] op_sel_hi:[1,0]
	v_pk_mul_f32 v[42:43], v[142:143], v[26:27] op_sel_hi:[1,0]
	v_pk_mul_f32 v[44:45], v[144:145], v[26:27] op_sel_hi:[1,0]
	v_pk_mul_f32 v[46:47], v[152:153], v[26:27] op_sel_hi:[1,0]
	v_pk_mul_f32 v[48:49], v[154:155], v[26:27] op_sel_hi:[1,0]
	v_pk_mul_f32 v[50:51], v[158:159], v[28:29] op_sel_hi:[1,0]
	v_pk_mul_f32 v[52:53], v[160:161], v[28:29] op_sel_hi:[1,0]
	v_pk_mul_f32 v[54:55], v[162:163], v[28:29] op_sel_hi:[1,0]
	v_pk_mul_f32 v[56:57], v[156:157], v[28:29] op_sel_hi:[1,0]
	v_pk_mul_f32 v[58:59], v[164:165], v[28:29] op_sel_hi:[1,0]
	v_pk_mul_f32 v[60:61], v[146:147], v[28:29] op_sel_hi:[1,0]
	v_pk_mul_f32 v[62:63], v[166:167], v[28:29] op_sel_hi:[1,0]
	v_pk_mul_f32 v[64:65], v[140:141], v[28:29] op_sel_hi:[1,0]
	v_pk_mul_f32 v[28:29], v[2:3], v[32:33]
	v_pk_mul_f32 v[26:27], v[0:1], v[30:31]
	v_pk_mul_f32 v[32:33], v[6:7], v[38:39]
	v_pk_mul_f32 v[30:31], v[4:5], v[34:35]
	v_pk_mul_f32 v[44:45], v[10:11], v[44:45]
	v_pk_mul_f32 v[42:43], v[8:9], v[42:43]
	v_pk_mul_f32 v[48:49], v[14:15], v[48:49]
	v_pk_mul_f32 v[46:47], v[12:13], v[46:47]
	v_pk_mul_f32 v[52:53], v[2:3], v[52:53]
	v_pk_mul_f32 v[50:51], v[0:1], v[50:51]
	v_pk_mul_f32 v[56:57], v[6:7], v[56:57]
	v_pk_mul_f32 v[54:55], v[4:5], v[54:55]
	v_pk_mul_f32 v[60:61], v[10:11], v[60:61]
	v_pk_mul_f32 v[58:59], v[8:9], v[58:59]
	v_pk_mul_f32 v[64:65], v[14:15], v[64:65]
	v_pk_mul_f32 v[62:63], v[12:13], v[62:63]
	global_store_dwordx4 v[36:37], v[26:29], off nt
	global_store_dwordx4 v[36:37], v[30:33], off offset:1024 nt
	global_store_dwordx4 v[36:37], v[42:45], off offset:2048 nt
	global_store_dwordx4 v[36:37], v[46:49], off offset:3072 nt
	global_store_dwordx4 v[40:41], v[50:53], off nt
	global_store_dwordx4 v[40:41], v[54:57], off offset:1024 nt
	global_store_dwordx4 v[40:41], v[58:61], off offset:2048 nt
	global_store_dwordx4 v[40:41], v[62:65], off offset:3072 nt
	s_cbranch_scc0 .LBB0_1323

; __device__ __forceinline__ f32x4 unpack4(unsigned long long w) { const unsigned lo = (unsigned)w, hi = (unsigned)(w >> 32); return (f32x4){__uint_as_float(lo << 16), __uint_as_float(lo & 0xffff0000u), __uint_as_float(hi << 16), __uint_as_float(hi & 0xffff0000u)}; }
; template <int MODE, int NR>
; __device__ __forceinline__ void norm_rows(const float* X32, bf16* X, bf16* H, float* out32, const f32x4 (&mul)[4], const f32x4 (&sh)[4], int lane) {
;     ...
;         unsigned long long raw[NR][4];
; #pragma unroll
;         for (int r = 0; r < NR; ++r) { const unsigned long long* xr = (const unsigned long long*)(X + (size_t)r * D) + lane;
; #pragma unroll
;             for (int j = 0; j < 4; ++j) raw[r][j] = xr[64 * j]; }
; #pragma unroll
;         for (int r = 0; r < NR; ++r) { f32x4 v[4]; float s = 0.f;
; #pragma unroll
;             for (int j = 0; j < 4; ++j) { v[j] = unpack4(raw[r][j]); s += (v[j].x * v[j].x + v[j].y * v[j].y) + (v[j].z * v[j].z + v[j].w * v[j].w); }
;             const float rstd = rsqrtf(wave_sum(s) * (1.f / D) + EPS);
;             if constexpr (MODE == 2) { f32x4* o = (f32x4*)(out32 + (size_t)r * D) + lane;
; #pragma unroll
;                 for (int j = 0; j < 4; ++j) o[64 * j] = v[j] * rstd * mul[j];
; __device__ __forceinline__ void phase_final(const bf16* X, float* out, const float* nw, int gw, int NGW, int lane) {
;     ...
;     for (int sr = gw; sr < MS; sr += NGW) { const size_t ro = (size_t)(MP + sr) * D; norm_rows<2, 1>(nullptr, (bf16*)X + ro, nullptr, out + ro, w4, w4, lane); }
.LBB0_1326:
	global_load_dwordx2 v[22:23], v[20:21], off
	global_load_dwordx2 v[24:25], v[20:21], off offset:512
	global_load_dwordx2 v[26:27], v[20:21], off offset:1024
	global_load_dwordx2 v[28:29], v[20:21], off offset:1536
	s_add_i32 s2, s2, s96
	v_lshl_add_u64 v[20:21], v[20:21], 0, s[4:5]
	s_cmpk_lt_i32 s2, 0x80
	s_waitcnt vmcnt(0) lgkmcnt(0)
	v_lshlrev_b32_e32 v30, 16, v22
	v_and_b32_e32 v31, 0xffff0000, v22
	v_lshlrev_b32_e32 v22, 16, v23
	v_and_b32_e32 v23, 0xffff0000, v23
	v_lshlrev_b32_e32 v32, 16, v24
	v_and_b32_e32 v33, 0xffff0000, v24
	v_lshlrev_b32_e32 v24, 16, v25
	v_and_b32_e32 v25, 0xffff0000, v25
	v_lshlrev_b32_e32 v34, 16, v26
	v_and_b32_e32 v35, 0xffff0000, v26
	v_lshlrev_b32_e32 v26, 16, v27
	v_and_b32_e32 v27, 0xffff0000, v27
	v_mul_f32_e32 v19, v31, v31
	v_mul_f32_e32 v38, v23, v23
	v_mul_f32_e32 v39, v33, v33
	v_mul_f32_e32 v40, v25, v25
	v_lshlrev_b32_e32 v36, 16, v28
	v_and_b32_e32 v37, 0xffff0000, v28
	v_lshlrev_b32_e32 v28, 16, v29
	v_and_b32_e32 v29, 0xffff0000, v29
	v_mul_f32_e32 v41, v35, v35
	v_mul_f32_e32 v42, v27, v27
	v_fmac_f32_e32 v19, v30, v30
	v_fmac_f32_e32 v38, v22, v22
	v_fmac_f32_e32 v39, v32, v32
	v_fmac_f32_e32 v40, v24, v24
	v_mul_f32_e32 v43, v37, v37
	v_mul_f32_e32 v44, v29, v29
	v_fmac_f32_e32 v41, v34, v34
	v_fmac_f32_e32 v42, v26, v26
	v_add_f32_e32 v19, v19, v38
	v_add_f32_e32 v38, v39, v40
	v_fmac_f32_e32 v43, v36, v36
	v_fmac_f32_e32 v44, v28, v28
	v_add_f32_e32 v39, v41, v42
	v_add_f32_e32 v19, v19, v38
	v_add_f32_e32 v40, v43, v44
	v_add_f32_e32 v19, v19, v39
	v_add_f32_e32 v19, v19, v40
	ds_swizzle_b32 v38, v19 offset:swizzle(SWAP,1)
	s_waitcnt lgkmcnt(0)
	v_add_f32_e32 v19, v19, v38
	ds_swizzle_b32 v38, v19 offset:swizzle(SWAP,2)
	s_waitcnt lgkmcnt(0)
	v_add_f32_e32 v19, v19, v38
	ds_swizzle_b32 v38, v19 offset:swizzle(SWAP,4)
	s_waitcnt lgkmcnt(0)
	v_add_f32_e32 v19, v19, v38
	ds_swizzle_b32 v38, v19 offset:swizzle(SWAP,8)
	s_waitcnt lgkmcnt(0)
	v_add_f32_e32 v19, v19, v38
	ds_swizzle_b32 v38, v19 offset:swizzle(SWAP,16)
	s_waitcnt lgkmcnt(0)
	v_add_f32_e32 v19, v19, v38
	v_mov_b32_e32 v38, v19
	s_nop 1
	v_permlane32_swap_b32_e32 v19, v38
	v_add_f32_e32 v19, v19, v38
	v_fmamk_f32 v19, v19, 0x3a800000, v18
	v_mul_f32_e32 v38, 0x4b800000, v19
	v_cmp_gt_f32_e32 vcc, s0, v19
	s_nop 1
	v_cndmask_b32_e32 v19, v19, v38, vcc
	v_rsq_f32_e32 v19, v19
	s_nop 0
	v_mul_f32_e32 v38, 0x45800000, v19
	v_cndmask_b32_e32 v38, v19, v38, vcc
	v_pk_mul_f32 v[30:31], v[30:31], v[38:39] op_sel_hi:[1,0]
	v_pk_mul_f32 v[22:23], v[22:23], v[38:39] op_sel_hi:[1,0]
	v_pk_mul_f32 v[32:33], v[32:33], v[38:39] op_sel_hi:[1,0]
	v_pk_mul_f32 v[40:41], v[24:25], v[38:39] op_sel_hi:[1,0]
	v_pk_mul_f32 v[34:35], v[34:35], v[38:39] op_sel_hi:[1,0]
	v_pk_mul_f32 v[42:43], v[26:27], v[38:39] op_sel_hi:[1,0]
	v_pk_mul_f32 v[44:45], v[36:37], v[38:39] op_sel_hi:[1,0]
	v_pk_mul_f32 v[36:37], v[28:29], v[38:39] op_sel_hi:[1,0]
	v_pk_mul_f32 v[24:25], v[2:3], v[22:23]
	v_pk_mul_f32 v[22:23], v[0:1], v[30:31]
	v_pk_mul_f32 v[28:29], v[6:7], v[40:41]
	v_pk_mul_f32 v[26:27], v[4:5], v[32:33]
	v_pk_mul_f32 v[32:33], v[10:11], v[42:43]
	v_pk_mul_f32 v[30:31], v[8:9], v[34:35]
	v_pk_mul_f32 v[36:37], v[14:15], v[36:37]
	v_pk_mul_f32 v[34:35], v[12:13], v[44:45]
	global_store_dwordx4 v[16:17], v[22:25], off offset:-3072 nt
	global_store_dwordx4 v[16:17], v[26:29], off offset:-2048 nt
	global_store_dwordx4 v[16:17], v[30:33], off offset:-1024 nt
	global_store_dwordx4 v[16:17], v[34:37], off nt
	v_lshl_add_u64 v[16:17], v[16:17], 0, s[6:7]
	s_cbranch_scc1 .LBB0_1326
